# RES epilogue residual loads lane-transposed (coalesced) with in-place inverse ds_bpermute; entry early-exit via trampoline
# baseline (speedup 1.0000x reference)
; __device__ __forceinline__ u32x4 pack8(const f32x4& v0, const f32x4& v1) { u32x4 w; w.x = cvt_pk_bf16(v0[0], v0[1]); w.y = cvt_pk_bf16(v0[2], v0[3]); w.z = cvt_pk_bf16(v1[0], v1[1]); w.w = cvt_pk_bf16(v1[2], v1[3]); return w; }
; __device__ __forceinline__ void epi_run(const Epi& E, f32x4 (&acc)[2][2][4][2], const Unit& u, int wr, int wc, int fr, int fq) {
;     ...
;     } else if (mode == MODE_E) {
; #pragma unroll
;         for (int ai = 0; ai < 2; ++ai)
; #pragma unroll
;             for (int m = 0; m < 4; ++m)
; #pragma unroll
;                 for (int bj = 0; bj < 2; ++bj) *(u32x4*)(E.C16 + (size_t)(row0 + ai * 128 + m * 16) * D + col0 + bj * 128) = pack8(acc[ai][bj][m][0], acc[ai][bj][m][1]);
.LBB0_268:
	s_cmp_gt_i32 s83, 4
	s_cbranch_scc0 .LBB0_275
	s_mov_b64 s[8:9], 0
	s_mov_b64 s[44:45], -1
	s_cmp_gt_i32 s83, 5
	s_mov_b64 s[96:97], 0
	s_cbranch_scc0 .LBB0_276
	s_cmp_eq_u32 s83, 6
	s_mov_b64 s[96:97], -1
	s_cbranch_scc0 .LBB0_297
	v_lshrrev_b32_e32 v140, 2, v201
	v_and_b32_e32 v141, 3, v201
	v_lshl_add_u32 v154, v141, 4, v140
	v_lshlrev_b32_e32 v154, 2, v154
	v_and_b32_e32 v142, 15, v201
	v_sub_u32_e32 v140, v140, v142
	v_lshrrev_b32_e32 v142, 4, v201
	v_sub_u32_e32 v141, v141, v142
	v_lshlrev_b32_e32 v141, 4, v141
	v_lshlrev_b32_e32 v140, 11, v140
	v_add_u32_e32 v152, v140, v141
	v_ashrrev_i32_e32 v153, 31, v152
	v_ashrrev_i32_e32 v211, 31, v210
	v_ashrrev_i32_e32 v213, 31, v212
	v_lshlrev_b64 v[134:135], 11, v[210:211]
	v_lshl_add_u64 v[134:135], s[62:63], 0, v[134:135]
	v_lshlrev_b64 v[136:137], 1, v[212:213]
	s_waitcnt lgkmcnt(0)
	v_cvt_pk_bf16_f32 v130, v126, v127
	v_cvt_pk_bf16_f32 v131, v128, v129
	v_cvt_pk_bf16_f32 v132, v122, v123
	v_cvt_pk_bf16_f32 v133, v124, v125
	v_lshl_add_u64 v[134:135], v[134:135], 0, v[136:137]
	v_lshl_add_u64 v[148:149], v[134:135], 0, v[152:153]
	ds_bpermute_b32 v140, v154, v130
	ds_bpermute_b32 v141, v154, v131
	ds_bpermute_b32 v142, v154, v132
	ds_bpermute_b32 v143, v154, v133
	s_mov_b32 s2, 0x40000
	s_mov_b64 s[20:21], 0x40000
	v_cvt_pk_bf16_f32 v130, v118, v119
	v_cvt_pk_bf16_f32 v131, v120, v121
	v_cvt_pk_bf16_f32 v132, v114, v115
	v_cvt_pk_bf16_f32 v133, v116, v117
	s_waitcnt lgkmcnt(0)
	global_store_dwordx4 v[148:149], v[140:143], off
	v_lshl_add_u64 v[150:151], v[134:135], 0, v[152:153]
	ds_bpermute_b32 v144, v154, v130
	ds_bpermute_b32 v145, v154, v131
	ds_bpermute_b32 v146, v154, v132
	ds_bpermute_b32 v147, v154, v133
	s_mov_b64 s[96:97], 0
	s_mov_b64 s[44:45], 0
	v_or_b32_e32 v130, 16, v210
	v_ashrrev_i32_e32 v131, 31, v130
	v_lshlrev_b64 v[138:139], 11, v[130:131]
	v_lshl_add_u64 v[138:139], s[62:63], 0, v[138:139]
	v_cvt_pk_bf16_f32 v130, v110, v111
	v_cvt_pk_bf16_f32 v131, v112, v113
	v_cvt_pk_bf16_f32 v132, v106, v107
	v_cvt_pk_bf16_f32 v133, v108, v109
	v_lshl_add_u64 v[138:139], v[138:139], 0, v[136:137]
	s_waitcnt lgkmcnt(0)
	global_store_dwordx4 v[150:151], v[144:147], off offset:256
	v_lshl_add_u64 v[148:149], v[138:139], 0, v[152:153]
	ds_bpermute_b32 v140, v154, v130
	ds_bpermute_b32 v141, v154, v131
	ds_bpermute_b32 v142, v154, v132
	ds_bpermute_b32 v143, v154, v133
	s_nop 1
	v_cvt_pk_bf16_f32 v130, v102, v103
	v_cvt_pk_bf16_f32 v131, v104, v105
	v_cvt_pk_bf16_f32 v132, v94, v95
	v_cvt_pk_bf16_f32 v133, v96, v97
	s_waitcnt lgkmcnt(0)
	global_store_dwordx4 v[148:149], v[140:143], off
	v_lshl_add_u64 v[150:151], v[138:139], 0, v[152:153]
	ds_bpermute_b32 v144, v154, v130
	ds_bpermute_b32 v145, v154, v131
	ds_bpermute_b32 v146, v154, v132
	ds_bpermute_b32 v147, v154, v133
	s_nop 1
	v_or_b32_e32 v130, 32, v210
	v_ashrrev_i32_e32 v131, 31, v130
	v_lshlrev_b64 v[138:139], 11, v[130:131]
	v_lshl_add_u64 v[138:139], s[62:63], 0, v[138:139]
	v_cvt_pk_bf16_f32 v130, v98, v99
	v_cvt_pk_bf16_f32 v131, v100, v101
	v_cvt_pk_bf16_f32 v132, v90, v91
	v_cvt_pk_bf16_f32 v133, v92, v93
	v_lshl_add_u64 v[138:139], v[138:139], 0, v[136:137]
	s_waitcnt lgkmcnt(0)
	global_store_dwordx4 v[150:151], v[144:147], off offset:256
	v_lshl_add_u64 v[148:149], v[138:139], 0, v[152:153]
	ds_bpermute_b32 v140, v154, v130
	ds_bpermute_b32 v141, v154, v131
	ds_bpermute_b32 v142, v154, v132
	ds_bpermute_b32 v143, v154, v133
	s_nop 1
	v_cvt_pk_bf16_f32 v130, v86, v87
	v_cvt_pk_bf16_f32 v131, v88, v89
	v_cvt_pk_bf16_f32 v132, v78, v79
	v_cvt_pk_bf16_f32 v133, v80, v81
	s_waitcnt lgkmcnt(0)
	global_store_dwordx4 v[148:149], v[140:143], off
	v_lshl_add_u64 v[150:151], v[138:139], 0, v[152:153]
	ds_bpermute_b32 v144, v154, v130
	ds_bpermute_b32 v145, v154, v131
	ds_bpermute_b32 v146, v154, v132
	ds_bpermute_b32 v147, v154, v133
	s_nop 1
	v_or_b32_e32 v130, 48, v210
	v_ashrrev_i32_e32 v131, 31, v130
	v_lshlrev_b64 v[138:139], 11, v[130:131]
	v_lshl_add_u64 v[138:139], s[62:63], 0, v[138:139]
	v_cvt_pk_bf16_f32 v130, v82, v83
	v_cvt_pk_bf16_f32 v131, v84, v85
	v_cvt_pk_bf16_f32 v132, v74, v75
	v_cvt_pk_bf16_f32 v133, v76, v77
	v_lshl_add_u64 v[136:137], v[138:139], 0, v[136:137]
	s_waitcnt lgkmcnt(0)
	global_store_dwordx4 v[150:151], v[144:147], off offset:256
	v_lshl_add_u64 v[148:149], v[136:137], 0, v[152:153]
	ds_bpermute_b32 v140, v154, v130
	ds_bpermute_b32 v141, v154, v131
	ds_bpermute_b32 v142, v154, v132
	ds_bpermute_b32 v143, v154, v133
	v_add_co_u32_e32 v138, vcc, s2, v134
	s_nop 0
	v_cvt_pk_bf16_f32 v130, v70, v71
	v_cvt_pk_bf16_f32 v131, v72, v73
	v_cvt_pk_bf16_f32 v132, v66, v67
	v_cvt_pk_bf16_f32 v133, v68, v69
	s_waitcnt lgkmcnt(0)
; __device__ __forceinline__ u32x4 pack8(const f32x4& v0, const f32x4& v1) { u32x4 w; w.x = cvt_pk_bf16(v0[0], v0[1]); w.y = cvt_pk_bf16(v0[2], v0[3]); w.z = cvt_pk_bf16(v1[0], v1[1]); w.w = cvt_pk_bf16(v1[2], v1[3]); return w; }
; #define PG8_BAR __builtin_amdgcn_s_barrier()
; __device__ __forceinline__ void epi_run(const Epi& E, f32x4 (&acc)[2][2][4][2], const Unit& u, int wr, int wc, int fr, int fq) {
;     ...
;     } else if (mode == MODE_E) {
; #pragma unroll
;         for (int ai = 0; ai < 2; ++ai)
; #pragma unroll
;             for (int m = 0; m < 4; ++m)
; #pragma unroll
;                 for (int bj = 0; bj < 2; ++bj) *(u32x4*)(E.C16 + (size_t)(row0 + ai * 128 + m * 16) * D + col0 + bj * 128) = pack8(acc[ai][bj][m][0], acc[ai][bj][m][1]);
; __device__ __forceinline__ void gemm_phase(LAS unsigned char* lds, const Sched& S, const Epi& E) {
;     ...
;         if (wr == 0) PG8_BAR;
;         epi_run(E, acc, cur, wr, wc, fr, fq);
	global_store_dwordx4 v[148:149], v[140:143], off
	v_lshl_add_u64 v[150:151], v[136:137], 0, v[152:153]
	ds_bpermute_b32 v144, v154, v130
	ds_bpermute_b32 v145, v154, v131
	ds_bpermute_b32 v146, v154, v132
	ds_bpermute_b32 v147, v154, v133
	v_addc_co_u32_e32 v139, vcc, 0, v135, vcc
	s_nop 0
	v_cvt_pk_bf16_f32 v130, v62, v63
	v_cvt_pk_bf16_f32 v131, v64, v65
	v_cvt_pk_bf16_f32 v132, v58, v59
	v_cvt_pk_bf16_f32 v133, v60, v61
	s_mov_b32 s2, 0x48000
	v_lshl_add_u64 v[136:137], v[134:135], 0, s[20:21]
	s_waitcnt lgkmcnt(0)
	global_store_dwordx4 v[150:151], v[144:147], off offset:256
	v_lshl_add_u64 v[148:149], v[138:139], 0, v[152:153]
	ds_bpermute_b32 v140, v154, v130
	ds_bpermute_b32 v141, v154, v131
	ds_bpermute_b32 v142, v154, v132
	ds_bpermute_b32 v143, v154, v133
	v_add_co_u32_e32 v138, vcc, s2, v134
	s_nop 0
	v_cvt_pk_bf16_f32 v130, v54, v55
	v_cvt_pk_bf16_f32 v131, v56, v57
	v_cvt_pk_bf16_f32 v132, v50, v51
	v_cvt_pk_bf16_f32 v133, v52, v53
	s_waitcnt lgkmcnt(0)
	global_store_dwordx4 v[148:149], v[140:143], off
	v_lshl_add_u64 v[150:151], v[136:137], 0, v[152:153]
	ds_bpermute_b32 v144, v154, v130
	ds_bpermute_b32 v145, v154, v131
	ds_bpermute_b32 v146, v154, v132
	ds_bpermute_b32 v147, v154, v133
	s_mov_b64 s[20:21], 0x48000
	v_addc_co_u32_e32 v139, vcc, 0, v135, vcc
	v_cvt_pk_bf16_f32 v130, v46, v47
	v_cvt_pk_bf16_f32 v131, v48, v49
	v_cvt_pk_bf16_f32 v132, v42, v43
	v_cvt_pk_bf16_f32 v133, v44, v45
	s_mov_b32 s2, 0x50000
	v_lshl_add_u64 v[136:137], v[134:135], 0, s[20:21]
	s_waitcnt lgkmcnt(0)
	global_store_dwordx4 v[150:151], v[144:147], off offset:256
	v_lshl_add_u64 v[148:149], v[138:139], 0, v[152:153]
	ds_bpermute_b32 v140, v154, v130
	ds_bpermute_b32 v141, v154, v131
	ds_bpermute_b32 v142, v154, v132
	ds_bpermute_b32 v143, v154, v133
	v_add_co_u32_e32 v138, vcc, s2, v134
	s_nop 0
	v_cvt_pk_bf16_f32 v130, v38, v39
	v_cvt_pk_bf16_f32 v131, v40, v41
	v_cvt_pk_bf16_f32 v132, v34, v35
	v_cvt_pk_bf16_f32 v133, v36, v37
	s_waitcnt lgkmcnt(0)
	global_store_dwordx4 v[148:149], v[140:143], off
	v_lshl_add_u64 v[150:151], v[136:137], 0, v[152:153]
	ds_bpermute_b32 v144, v154, v130
	ds_bpermute_b32 v145, v154, v131
	ds_bpermute_b32 v146, v154, v132
	ds_bpermute_b32 v147, v154, v133
	s_mov_b64 s[20:21], 0x50000
	v_addc_co_u32_e32 v139, vcc, 0, v135, vcc
	v_cvt_pk_bf16_f32 v130, v30, v31
	v_cvt_pk_bf16_f32 v131, v32, v33
	v_cvt_pk_bf16_f32 v132, v26, v27
	v_cvt_pk_bf16_f32 v133, v28, v29
	v_lshl_add_u64 v[136:137], v[134:135], 0, s[20:21]
	s_waitcnt lgkmcnt(0)
	global_store_dwordx4 v[150:151], v[144:147], off offset:256
	v_lshl_add_u64 v[148:149], v[138:139], 0, v[152:153]
	ds_bpermute_b32 v140, v154, v130
	ds_bpermute_b32 v141, v154, v131
	ds_bpermute_b32 v142, v154, v132
	ds_bpermute_b32 v143, v154, v133
	s_mov_b64 s[20:21], 0x58000
	s_mov_b32 s2, 0x58000
	v_cvt_pk_bf16_f32 v130, v22, v23
	v_cvt_pk_bf16_f32 v131, v24, v25
	v_cvt_pk_bf16_f32 v132, v18, v19
	v_cvt_pk_bf16_f32 v133, v20, v21
	s_waitcnt lgkmcnt(0)
	global_store_dwordx4 v[148:149], v[140:143], off
	v_lshl_add_u64 v[150:151], v[136:137], 0, v[152:153]
	ds_bpermute_b32 v144, v154, v130
	ds_bpermute_b32 v145, v154, v131
	ds_bpermute_b32 v146, v154, v132
	ds_bpermute_b32 v147, v154, v133
	v_lshl_add_u64 v[136:137], v[134:135], 0, s[20:21]
	v_add_co_u32_e32 v134, vcc, s2, v134
	v_cvt_pk_bf16_f32 v130, v14, v15
	v_cvt_pk_bf16_f32 v131, v16, v17
	v_cvt_pk_bf16_f32 v132, v10, v11
	v_cvt_pk_bf16_f32 v133, v12, v13
	v_addc_co_u32_e32 v135, vcc, 0, v135, vcc
	s_waitcnt lgkmcnt(0)
	global_store_dwordx4 v[150:151], v[144:147], off offset:256
	v_lshl_add_u64 v[148:149], v[134:135], 0, v[152:153]
	ds_bpermute_b32 v140, v154, v130
	ds_bpermute_b32 v141, v154, v131
	ds_bpermute_b32 v142, v154, v132
	ds_bpermute_b32 v143, v154, v133
	s_nop 1
	v_cvt_pk_bf16_f32 v130, v6, v7
	v_cvt_pk_bf16_f32 v131, v8, v9
	v_cvt_pk_bf16_f32 v132, v2, v3
	v_cvt_pk_bf16_f32 v133, v4, v5
	s_waitcnt lgkmcnt(0)
	global_store_dwordx4 v[148:149], v[140:143], off
	v_lshl_add_u64 v[150:151], v[136:137], 0, v[152:153]
	ds_bpermute_b32 v144, v154, v130
	ds_bpermute_b32 v145, v154, v131
	ds_bpermute_b32 v146, v154, v132
	ds_bpermute_b32 v147, v154, v133
	s_waitcnt lgkmcnt(0)
	global_store_dwordx4 v[150:151], v[144:147], off offset:256
	s_and_b64 vcc, exec, s[8:9]
	s_cbranch_vccnz .LBB0_277
	s_branch .LBB0_298
.Lmy_tramp456:
	s_branch .LBB0_456
.LBB0_272:
	s_barrier
	v_lshl_add_u32 v210, s95, 8, v239
	s_cmp_lt_i32 s83, 3
	v_lshl_or_b32 v212, s23, 8, v242
	s_cbranch_scc0 .LBB0_268

; __device__ __forceinline__ void epi_run(const Epi& E, f32x4 (&acc)[2][2][4][2], const Unit& u, int wr, int wc, int fr, int fq) {
;     ...
;     } else if (mode == MODE_RES) {
;         float* sslot = E.ssq_out + (size_t)(u.pn * 4 + wc) * M;
;         u32x4 x[2][4][2];
; #pragma unroll
;         for (int ai = 0; ai < 2; ++ai)
; #pragma unroll
;             for (int m = 0; m < 4; ++m)
; #pragma unroll
;                 for (int bj = 0; bj < 2; ++bj) x[ai][m][bj] = *(const u32x4*)(E.xin16 + (size_t)(row0 + ai * 128 + m * 16) * D + col0 + bj * 128);
.LBB0_277:
	s_cmp_gt_i32 s83, 3
	s_mov_b64 s[8:9], -1
	s_cbranch_scc0 .LBB0_295
	v_ashrrev_i32_e32 v213, 31, v212
	v_lshlrev_b64 v[228:229], 1, v[212:213]
	v_ashrrev_i32_e32 v211, 31, v210
	s_waitcnt lgkmcnt(0)
	v_lshl_add_u64 v[130:131], s[48:49], 0, v[228:229]
	v_lshrrev_b32_e32 v246, 2, v201
	v_and_b32_e32 v247, 3, v201
	v_and_b32_e32 v248, 15, v201
	v_lshrrev_b32_e32 v249, 4, v201
	v_sub_u32_e32 v246, v246, v248
	v_sub_u32_e32 v247, v247, v249
	v_lshl_add_u32 v249, v248, 2, v249
	v_lshlrev_b32_e32 v249, 2, v249
	v_lshlrev_b32_e32 v247, 4, v247
	v_lshl_add_u32 v244, v246, 11, v247
	v_ashrrev_i32_e32 v245, 31, v244
	v_lshl_add_u64 v[130:131], v[130:131], 0, v[244:245]
	v_lshlrev_b64 v[230:231], 11, v[210:211]
	v_lshl_add_u64 v[132:133], v[130:131], 0, v[230:231]
	global_load_dwordx4 v[190:193], v[132:133], off
	global_load_dwordx4 v[186:189], v[132:133], off offset:256
	v_or_b32_e32 v132, 16, v210
	v_ashrrev_i32_e32 v133, 31, v132
	v_lshlrev_b64 v[226:227], 11, v[132:133]
	v_lshl_add_u64 v[132:133], v[130:131], 0, v[226:227]
	global_load_dwordx4 v[182:185], v[132:133], off
	global_load_dwordx4 v[178:181], v[132:133], off offset:256
	v_or_b32_e32 v132, 32, v210
	v_ashrrev_i32_e32 v133, 31, v132
	v_lshlrev_b64 v[224:225], 11, v[132:133]
	v_lshl_add_u64 v[132:133], v[130:131], 0, v[224:225]
	global_load_dwordx4 v[174:177], v[132:133], off
	global_load_dwordx4 v[170:173], v[132:133], off offset:256
	v_or_b32_e32 v132, 48, v210
	v_ashrrev_i32_e32 v133, 31, v132
	s_mov_b64 s[20:21], 0x40000
	v_lshlrev_b64 v[222:223], 11, v[132:133]
	v_lshl_add_u64 v[220:221], v[230:231], 0, s[20:21]
	s_mov_b64 s[20:21], 0x48000
	v_lshl_add_u64 v[132:133], v[130:131], 0, v[222:223]
	v_lshl_add_u64 v[218:219], v[230:231], 0, s[20:21]
	s_mov_b64 s[20:21], 0x50000
	global_load_dwordx4 v[166:169], v[132:133], off
	global_load_dwordx4 v[162:165], v[132:133], off offset:256
	v_lshl_add_u64 v[132:133], v[130:131], 0, v[220:221]
	v_lshl_add_u64 v[216:217], v[230:231], 0, s[20:21]
	s_mov_b64 s[20:21], 0x58000
	global_load_dwordx4 v[158:161], v[132:133], off
	global_load_dwordx4 v[154:157], v[132:133], off offset:256
	v_lshl_add_u64 v[132:133], v[130:131], 0, v[218:219]
	v_lshl_add_u64 v[214:215], v[230:231], 0, s[20:21]
	global_load_dwordx4 v[150:153], v[132:133], off
	global_load_dwordx4 v[146:149], v[132:133], off offset:256
	v_lshl_add_u64 v[132:133], v[130:131], 0, v[216:217]
	v_lshl_add_u64 v[130:131], v[130:131], 0, v[214:215]
	global_load_dwordx4 v[142:145], v[132:133], off
	global_load_dwordx4 v[138:141], v[132:133], off offset:256
	global_load_dwordx4 v[134:137], v[130:131], off
	s_nop 0
	global_load_dwordx4 v[130:133], v[130:131], off offset:256
	v_lshl_add_u64 v[230:231], s[78:79], 0, v[230:231]
	v_lshl_add_u64 v[228:229], v[230:231], 0, v[228:229]
	v_cmp_lt_i32_e32 vcc, v233, v203
	s_lshl_b32 s2, s23, 2
	v_readlane_b32 s8, v250, 29
	v_cndmask_b32_e32 v0, v201, v233, vcc
	v_lshlrev_b32_e32 v0, 2, v0
	v_cmp_lt_i32_e32 vcc, v234, v203
	s_or_b32 s8, s2, s8
	s_ashr_i32 s9, s8, 31
	v_cndmask_b32_e32 v243, v201, v234, vcc
	v_lshlrev_b32_e32 v243, 2, v243
	s_lshl_b64 s[8:9], s[8:9], 16
	s_add_u32 s8, s76, s8
	s_addc_u32 s9, s77, s9
	s_waitcnt vmcnt(0)
; __device__ __forceinline__ float bf_lo(unsigned w) { return __uint_as_float(w << 16); }
; __device__ __forceinline__ float bf_hi(unsigned w) { return __uint_as_float(w & 0xffff0000u); }
; __device__ __forceinline__ u32x4 pack8(const f32x4& v0, const f32x4& v1) { u32x4 w; w.x = cvt_pk_bf16(v0[0], v0[1]); w.y = cvt_pk_bf16(v0[2], v0[3]); w.z = cvt_pk_bf16(v1[0], v1[1]); w.w = cvt_pk_bf16(v1[2], v1[3]); return w; }
; __device__ __forceinline__ float sumsq8(const f32x4& v0, const f32x4& v1) { return (v0[0] * v0[0] + v0[1] * v0[1]) + (v0[2] * v0[2] + v0[3] * v0[3]) + (v1[0] * v1[0] + v1[1] * v1[1]) + (v1[2] * v1[2] + v1[3] * v1[3]); }
; __device__ __forceinline__ void epi_run(const Epi& E, f32x4 (&acc)[2][2][4][2], const Unit& u, int wr, int wc, int fr, int fq) {
;     ...
;                 for (int bj = 0; bj < 2; ++bj) x[ai][m][bj] = *(const u32x4*)(E.xin16 + (size_t)(row0 + ai * 128 + m * 16) * D + col0 + bj * 128);
; #pragma unroll
;         for (int ai = 0; ai < 2; ++ai) {
; #pragma unroll
;             for (int m = 0; m < 4; ++m) { const int row = row0 + ai * 128 + m * 16; float sq = 0.f;
; #pragma unroll
;                 for (int bj = 0; bj < 2; ++bj) { const u32x4 xx = x[ai][m][bj];
;                     const f32x4 x0 = (f32x4){bf_lo(xx.x), bf_hi(xx.x), bf_lo(xx.y), bf_hi(xx.y)} + acc[ai][bj][m][0], x1 = (f32x4){bf_lo(xx.z), bf_hi(xx.z), bf_lo(xx.w), bf_hi(xx.w)} + acc[ai][bj][m][1];
;                     sq += sumsq8(x0, x1); *(u32x4*)(E.xout16 + (size_t)row * D + col0 + bj * 128) = pack8(x0, x1); }
;                 sq += __shfl_xor(sq, 16); sq += __shfl_xor(sq, 32); if (fq == 0) sslot[row] = sq; }
	ds_bpermute_b32 v190, v249, v190
	ds_bpermute_b32 v191, v249, v191
	ds_bpermute_b32 v192, v249, v192
	ds_bpermute_b32 v193, v249, v193
	ds_bpermute_b32 v186, v249, v186
	ds_bpermute_b32 v187, v249, v187
	ds_bpermute_b32 v188, v249, v188
	ds_bpermute_b32 v189, v249, v189
	ds_bpermute_b32 v182, v249, v182
	ds_bpermute_b32 v183, v249, v183
	ds_bpermute_b32 v184, v249, v184
	ds_bpermute_b32 v185, v249, v185
	ds_bpermute_b32 v178, v249, v178
	ds_bpermute_b32 v179, v249, v179
	ds_bpermute_b32 v180, v249, v180
	ds_bpermute_b32 v181, v249, v181
	ds_bpermute_b32 v174, v249, v174
	ds_bpermute_b32 v175, v249, v175
	ds_bpermute_b32 v176, v249, v176
	ds_bpermute_b32 v177, v249, v177
	ds_bpermute_b32 v170, v249, v170
	ds_bpermute_b32 v171, v249, v171
	ds_bpermute_b32 v172, v249, v172
	ds_bpermute_b32 v173, v249, v173
	ds_bpermute_b32 v166, v249, v166
	ds_bpermute_b32 v167, v249, v167
	ds_bpermute_b32 v168, v249, v168
	ds_bpermute_b32 v169, v249, v169
	ds_bpermute_b32 v162, v249, v162
	ds_bpermute_b32 v163, v249, v163
	ds_bpermute_b32 v164, v249, v164
	ds_bpermute_b32 v165, v249, v165
	ds_bpermute_b32 v158, v249, v158
	ds_bpermute_b32 v159, v249, v159
	ds_bpermute_b32 v160, v249, v160
	ds_bpermute_b32 v161, v249, v161
	ds_bpermute_b32 v154, v249, v154
	ds_bpermute_b32 v155, v249, v155
	ds_bpermute_b32 v156, v249, v156
	ds_bpermute_b32 v157, v249, v157
	ds_bpermute_b32 v150, v249, v150
	ds_bpermute_b32 v151, v249, v151
	ds_bpermute_b32 v152, v249, v152
	ds_bpermute_b32 v153, v249, v153
	ds_bpermute_b32 v146, v249, v146
	ds_bpermute_b32 v147, v249, v147
	ds_bpermute_b32 v148, v249, v148
	ds_bpermute_b32 v149, v249, v149
	ds_bpermute_b32 v142, v249, v142
	ds_bpermute_b32 v143, v249, v143
	ds_bpermute_b32 v144, v249, v144
	ds_bpermute_b32 v145, v249, v145
	ds_bpermute_b32 v138, v249, v138
	ds_bpermute_b32 v139, v249, v139
	ds_bpermute_b32 v140, v249, v140
	ds_bpermute_b32 v141, v249, v141
	ds_bpermute_b32 v134, v249, v134
	ds_bpermute_b32 v135, v249, v135
	ds_bpermute_b32 v136, v249, v136
	ds_bpermute_b32 v137, v249, v137
	ds_bpermute_b32 v130, v249, v130
	ds_bpermute_b32 v131, v249, v131
	ds_bpermute_b32 v132, v249, v132
	ds_bpermute_b32 v133, v249, v133
	s_waitcnt lgkmcnt(0)
	v_lshlrev_b32_e32 v244, 16, v190
	v_and_b32_e32 v245, 0xffff0000, v190
	v_lshlrev_b32_e32 v190, 16, v191
	v_and_b32_e32 v191, 0xffff0000, v191
	v_pk_add_f32 v[246:247], v[128:129], v[190:191]
	v_pk_add_f32 v[190:191], v[126:127], v[244:245]
	v_lshlrev_b32_e32 v244, 16, v192
	v_and_b32_e32 v245, 0xffff0000, v192
	v_lshlrev_b32_e32 v192, 16, v193
	v_and_b32_e32 v193, 0xffff0000, v193
	v_pk_add_f32 v[248:249], v[124:125], v[192:193]
	v_pk_add_f32 v[192:193], v[122:123], v[244:245]
	v_mul_f32_e32 v244, v191, v191
	v_mul_f32_e32 v245, v247, v247
	v_fmac_f32_e32 v244, v190, v190
	v_fmac_f32_e32 v245, v246, v246
	v_add_f32_e32 v244, v244, v245
	v_mul_f32_e32 v245, v193, v193
	v_fmac_f32_e32 v245, v192, v192
	v_cvt_pk_bf16_f32 v190, v190, v191
	v_cvt_pk_bf16_f32 v191, v246, v247
	v_cvt_pk_bf16_f32 v192, v192, v193
	v_cvt_pk_bf16_f32 v193, v248, v249
	v_lshrrev_b32_e32 v122, 2, v201
	v_and_b32_e32 v123, 3, v201
	v_lshl_add_u32 v246, v123, 4, v122
	v_lshlrev_b32_e32 v246, 2, v246
	v_and_b32_e32 v124, 15, v201
	v_sub_u32_e32 v122, v122, v124
	v_lshrrev_b32_e32 v124, 4, v201
	v_sub_u32_e32 v123, v123, v124
	v_lshlrev_b32_e32 v123, 4, v123
	v_lshlrev_b32_e32 v122, 11, v122
	v_add_u32_e32 v128, v122, v123
	v_ashrrev_i32_e32 v129, 31, v128
	v_lshl_add_u64 v[126:127], v[228:229], 0, v[128:129]
	ds_bpermute_b32 v122, v246, v190
	ds_bpermute_b32 v123, v246, v191
	ds_bpermute_b32 v124, v246, v192
	ds_bpermute_b32 v125, v246, v193
	v_add_f32_e32 v244, v245, v244
	v_mul_f32_e32 v245, v249, v249
	v_lshlrev_b32_e32 v190, 16, v186
	v_and_b32_e32 v191, 0xffff0000, v186
	v_lshlrev_b32_e32 v186, 16, v187
	v_and_b32_e32 v187, 0xffff0000, v187
	v_pk_add_f32 v[192:193], v[120:121], v[186:187]
	v_pk_add_f32 v[186:187], v[118:119], v[190:191]
	v_lshlrev_b32_e32 v190, 16, v188
	v_and_b32_e32 v191, 0xffff0000, v188
	v_lshlrev_b32_e32 v188, 16, v189
	v_and_b32_e32 v189, 0xffff0000, v189
	v_pk_add_f32 v[230:231], v[116:117], v[188:189]
	v_pk_add_f32 v[188:189], v[114:115], v[190:191]
	v_mul_f32_e32 v190, v187, v187
	v_mul_f32_e32 v191, v193, v193
	v_fmac_f32_e32 v190, v186, v186
	v_fmac_f32_e32 v191, v192, v192
	v_add_f32_e32 v190, v190, v191
	v_mul_f32_e32 v191, v189, v189
	v_fmac_f32_e32 v191, v188, v188
	v_add_f32_e32 v190, v191, v190
	v_mul_f32_e32 v191, v231, v231
	v_fmac_f32_e32 v245, v248, v248
	v_fmac_f32_e32 v191, v230, v230
	v_add_f32_e32 v244, v245, v244
	v_add_f32_e32 v190, v191, v190
	v_add_f32_e32 v190, v244, v190
	v_cvt_pk_bf16_f32 v186, v186, v187
	v_cvt_pk_bf16_f32 v187, v192, v193
	v_cvt_pk_bf16_f32 v188, v188, v189
	v_cvt_pk_bf16_f32 v189, v230, v231
	s_waitcnt lgkmcnt(0)
	global_store_dwordx4 v[126:127], v[122:125], off
	v_lshl_add_u64 v[126:127], v[228:229], 0, v[128:129]
	ds_bpermute_b32 v122, v246, v186
	ds_bpermute_b32 v123, v246, v187
	ds_bpermute_b32 v124, v246, v188
	ds_bpermute_b32 v125, v246, v189
	ds_bpermute_b32 v186, v0, v190
	s_waitcnt lgkmcnt(0)
	v_add_f32_e32 v188, v190, v186
	ds_bpermute_b32 v189, v243, v188
	v_lshl_add_u64 v[186:187], v[210:211], 2, s[8:9]
	s_and_saveexec_b64 s[8:9], s[40:41]
	s_cbranch_execz .LBB0_280
	s_waitcnt lgkmcnt(0)
	v_add_f32_e32 v188, v188, v189
	global_store_dword v[186:187], v188, off
